# v56 + MLA attention steps: first-half K-fragment LDS reads of k-steps 1..4 issued up front into spare VGPRs with counted lgkmcnt waits
# speedup vs baseline: 1.0140x; 1.0140x over previous
.LBB0_422:
	s_setprio 3
	s_add_i32 s41, s58, 0xfffc0000
	s_mov_b32 s30, s28
	s_mov_b32 s28, s40
	v_add_u32_e32 v0, s30, v134
	ds_read_b128 v[34:37], v0
	ds_read_b128 v[240:243], v0 offset:2048
	ds_read_b128 v[244:247], v0 offset:4096
	ds_read_b128 v[248:251], v0 offset:6144
	ds_read_b128 v[252:255], v0 offset:8192
	s_add_i32 s40, s57, -1
	s_and_b32 s41, s41, 0xf00000
	s_and_b32 s55, s40, 3
	s_lshl_b32 s78, s41, 1
	s_add_i32 s53, s29, 0
	v_lshl_add_u64 v[238:239], v[128:129], 0, s[78:79]
	s_lshl_b32 s40, s55, 16
	s_mov_b32 s41, s79
	s_add_i32 s54, s53, s27
	v_lshl_add_u64 v[238:239], v[238:239], 0, s[40:41]
	s_mov_b32 m0, s54
	s_andn2_b64 s[40:41], exec, s[38:39]
	global_load_lds_dwordx4 v[238:239], off
	s_andn2_b64 vcc, exec, s[38:39]
	s_cbranch_vccnz .LBB0_424
	v_lshl_add_u64 v[238:239], v[124:125], 0, s[78:79]
	s_mul_i32 s60, s55, 0x38000
	s_mov_b32 s61, s79
	s_add_i32 s56, s53, s5
	v_lshl_add_u64 v[238:239], v[238:239], 0, s[60:61]
	s_add_i32 m0, s56, 0x2000
	s_nop 0
	global_load_lds_dwordx4 v[238:239], off
.LBB0_424:
	s_lshl_b32 s55, s55, 15
	v_lshl_add_u64 v[238:239], v[130:131], 0, s[78:79]
	s_lshl_b32 s78, s55, 1
	v_lshl_add_u64 v[238:239], v[238:239], 0, s[78:79]
	s_add_i32 s55, s54, 0x3000
	v_lshl_add_u64 v[238:239], v[238:239], 0, s[24:25]
	s_mov_b32 m0, s55
	s_nop 0
	global_load_lds_dwordx4 v[238:239], off
	s_add_i32 s56, s30, 0
	v_exp_f32_e32 v153, v66
	v_exp_f32_e32 v166, v67
	v_exp_f32_e32 v167, v68
	v_exp_f32_e32 v168, v69
	v_exp_f32_e32 v169, v70
	v_exp_f32_e32 v170, v71
	v_exp_f32_e32 v171, v72
	v_exp_f32_e32 v172, v73
	s_waitcnt lgkmcnt(4)
	v_mfma_f32_32x32x16_bf16 v[82:97], v[34:37], v[118:121], v[50:65]
	v_exp_f32_e32 v173, v74
	v_exp_f32_e32 v174, v75
	v_exp_f32_e32 v175, v76
	v_exp_f32_e32 v176, v77
	v_exp_f32_e32 v177, v78
	v_exp_f32_e32 v178, v79
	s_waitcnt lgkmcnt(3)
	v_mfma_f32_32x32x16_bf16 v[82:97], v[240:243], v[114:117], v[82:97]
	v_exp_f32_e32 v179, v80
	v_exp_f32_e32 v180, v81
	s_waitcnt lgkmcnt(2)
	v_mfma_f32_32x32x16_bf16 v[82:97], v[244:247], v[110:113], v[82:97]
	s_waitcnt lgkmcnt(1)
	v_mfma_f32_32x32x16_bf16 v[82:97], v[248:251], v[106:109], v[82:97]
	v_add_f32_e32 v34, v141, v146
	v_add_f32_e32 v66, v138, v34
	ds_read_b128 v[34:37], v0 offset:10240
	s_setprio 2
	s_waitcnt lgkmcnt(1)
	v_mfma_f32_32x32x16_bf16 v[82:97], v[252:255], v[102:105], v[82:97]
	ds_read_b128 v[38:41], v0 offset:512
	ds_read_b128 v[42:45], v0 offset:2560
	ds_read_b128 v[46:49], v0 offset:4608
	ds_read_b128 v[154:157], v0 offset:6656
	ds_read_b128 v[158:161], v0 offset:8704
	ds_read_b128 v[162:165], v0 offset:10752
	v_add_f32_e32 v0, v142, v66
	v_add_f32_e32 v0, v143, v0
	v_add_f32_e32 v0, v147, v0
	v_add_f32_e32 v0, v148, v0
	v_add_f32_e32 v0, v151, v0
	v_add_f32_e32 v0, v137, v0
	s_waitcnt lgkmcnt(0)
	v_mfma_f32_32x32x16_bf16 v[66:81], v[38:41], v[118:121], v[50:65]
	v_add_f32_e32 v0, v139, v0
	v_add_f32_e32 v0, v140, v0
	v_add_f32_e32 v0, v144, v0
	v_add_f32_e32 v0, v145, v0
	v_add_f32_e32 v0, v149, v0
	v_add_f32_e32 v0, v150, v0
	v_add_f32_e32 v0, v152, v0
	v_mfma_f32_32x32x16_bf16 v[66:81], v[42:45], v[114:117], v[66:81]
	v_add_f32_e32 v0, v153, v0
	v_add_f32_e32 v0, v166, v0
	v_add_f32_e32 v0, v167, v0
	v_add_f32_e32 v0, v168, v0
	v_add_f32_e32 v0, v169, v0
	v_add_f32_e32 v0, v170, v0
	v_add_f32_e32 v0, v171, v0
	v_mfma_f32_32x32x16_bf16 v[66:81], v[46:49], v[110:113], v[66:81]
	v_add_f32_e32 v0, v172, v0
	v_add_f32_e32 v0, v173, v0
	v_add_f32_e32 v0, v174, v0
	v_add_f32_e32 v0, v175, v0
	v_add_f32_e32 v0, v176, v0
	v_add_f32_e32 v0, v177, v0
	v_add_f32_e32 v0, v178, v0
	v_mfma_f32_32x32x16_bf16 v[66:81], v[154:157], v[106:109], v[66:81]
	v_add_f32_e32 v181, v179, v0
	v_cvt_pk_bf16_f32 v38, v137, v139
	v_cvt_pk_bf16_f32 v39, v140, v144
	v_cvt_pk_bf16_f32 v40, v145, v149
	v_cvt_pk_bf16_f32 v41, v150, v152
	v_cvt_pk_bf16_f32 v42, v153, v166
	v_cvt_pk_bf16_f32 v43, v167, v168
	v_mfma_f32_32x32x16_bf16 v[66:81], v[158:161], v[102:105], v[66:81]
	v_cvt_pk_bf16_f32 v44, v169, v170
	v_cvt_pk_bf16_f32 v45, v171, v172
	v_cvt_pk_bf16_f32 v46, v173, v174
	v_cvt_pk_bf16_f32 v47, v175, v176
	v_cvt_pk_bf16_f32 v48, v177, v178
	v_cvt_pk_bf16_f32 v49, v179, v180
	v_mfma_f32_32x32x16_bf16 v[82:97], v[34:37], v[98:101], v[82:97]
	v_cvt_pk_bf16_f32 v34, v141, v146
	v_cvt_pk_bf16_f32 v35, v138, v142
	v_cvt_pk_bf16_f32 v36, v143, v147
	v_cvt_pk_bf16_f32 v37, v148, v151
	v_mfma_f32_32x32x16_bf16 v[66:81], v[162:165], v[98:101], v[66:81]
	s_add_i32 s59, s28, 0
	v_add_u32_e32 v0, s59, v133
	ds_read_b64_tr_b16 v[138:139], v0 offset:12288
	ds_read_b64_tr_b16 v[140:141], v0 offset:12800
	ds_read_b64_tr_b16 v[142:143], v0 offset:16384
	s_nop 5
	v_max_f32_e32 v137, v67, v67
	s_waitcnt lgkmcnt(1)
	v_mfma_f32_32x32x16_bf16 v[18:33], v[138:141], v[34:37], v[18:33]
	ds_read_b64_tr_b16 v[144:145], v0 offset:16896
	ds_read_b64_tr_b16 v[138:139], v0 offset:13312
	s_waitcnt lgkmcnt(1)
	v_mfma_f32_32x32x16_bf16 v[2:17], v[142:145], v[34:37], v[2:17]
	ds_read_b64_tr_b16 v[140:141], v0 offset:13824
	ds_read_b64_tr_b16 v[34:35], v0 offset:17408
	s_setprio 1
	s_waitcnt lgkmcnt(1)
	v_mfma_f32_32x32x16_bf16 v[18:33], v[138:141], v[38:41], v[18:33]
	ds_read_b64_tr_b16 v[36:37], v0 offset:17920
	ds_read_b64_tr_b16 v[138:139], v0 offset:14336
	s_waitcnt lgkmcnt(1)
	v_mfma_f32_32x32x16_bf16 v[2:17], v[34:37], v[38:41], v[2:17]
	ds_read_b64_tr_b16 v[140:141], v0 offset:14848
	ds_read_b64_tr_b16 v[34:35], v0 offset:15360
	ds_read_b64_tr_b16 v[36:37], v0 offset:15872
	ds_read_b64_tr_b16 v[38:39], v0 offset:18432
	ds_read_b64_tr_b16 v[40:41], v0 offset:18944
	ds_read_b64_tr_b16 v[142:143], v0 offset:19456
	ds_read_b64_tr_b16 v[144:145], v0 offset:19968
	s_waitcnt lgkmcnt(6)
	v_mfma_f32_32x32x16_bf16 v[18:33], v[138:141], v[42:45], v[18:33]
	v_max_f32_e32 v138, v83, v83
	v_max_f32_e32 v137, v138, v137
	v_max3_f32 v138, v82, v66, v84
	v_max3_f32 v137, v137, v85, v69
	v_max3_f32 v138, v138, v68, v86
	v_max3_f32 v137, v137, v87, v71
	s_waitcnt lgkmcnt(2)
	v_mfma_f32_32x32x16_bf16 v[2:17], v[38:41], v[42:45], v[2:17]
	v_max3_f32 v38, v138, v70, v88
	v_max3_f32 v39, v137, v89, v73
	v_max3_f32 v38, v38, v72, v90
	v_max3_f32 v39, v39, v91, v75
	v_max3_f32 v38, v38, v74, v92
	v_max3_f32 v39, v39, v93, v77
	v_max3_f32 v38, v38, v76, v94
	v_mfma_f32_32x32x16_bf16 v[18:33], v[34:37], v[46:49], v[18:33]
	v_max3_f32 v34, v39, v95, v79
	v_max3_f32 v35, v38, v78, v96
	v_max3_f32 v34, v34, v97, v81
	v_add_f32_e32 v36, v180, v181
	v_max3_f32 v34, v35, v80, v34
	v_add_f32_e32 v136, v136, v36
	v_cmp_lt_f32_e32 vcc, s33, v34
	s_waitcnt lgkmcnt(0)
	v_mfma_f32_32x32x16_bf16 v[2:17], v[142:145], v[46:49], v[2:17]
	s_cbranch_vccz .LBB0_426
	v_mov_b32_e32 v35, v34
	s_nop 1
	v_permlane32_swap_b32 v34, v35
	s_nop 1
	s_nop 0
	v_max3_f32 v36, v34, v35, 0
	v_exp_f32_e64 v38, -v36
	v_add_f32_e32 v135, v135, v36
	v_xor_b32_e32 v34, 0x80000000, v135
	v_pk_add_f32 v[82:83], v[82:83], v[36:37] op_sel_hi:[1,0] neg_lo:[0,1] neg_hi:[0,1]
	v_pk_add_f32 v[84:85], v[84:85], v[36:37] op_sel_hi:[1,0] neg_lo:[0,1] neg_hi:[0,1]
	v_pk_add_f32 v[86:87], v[86:87], v[36:37] op_sel_hi:[1,0] neg_lo:[0,1] neg_hi:[0,1]
	v_pk_add_f32 v[88:89], v[88:89], v[36:37] op_sel_hi:[1,0] neg_lo:[0,1] neg_hi:[0,1]
	v_pk_add_f32 v[90:91], v[90:91], v[36:37] op_sel_hi:[1,0] neg_lo:[0,1] neg_hi:[0,1]
	v_pk_add_f32 v[92:93], v[92:93], v[36:37] op_sel_hi:[1,0] neg_lo:[0,1] neg_hi:[0,1]
	v_pk_add_f32 v[94:95], v[94:95], v[36:37] op_sel_hi:[1,0] neg_lo:[0,1] neg_hi:[0,1]
	v_pk_add_f32 v[96:97], v[96:97], v[36:37] op_sel_hi:[1,0] neg_lo:[0,1] neg_hi:[0,1]
	v_sub_f32_e32 v81, v81, v36
	v_sub_f32_e32 v80, v80, v36
	v_sub_f32_e32 v79, v79, v36
	v_sub_f32_e32 v78, v78, v36
	v_sub_f32_e32 v77, v77, v36
	v_sub_f32_e32 v76, v76, v36
	v_sub_f32_e32 v75, v75, v36
	v_sub_f32_e32 v74, v74, v36
	v_sub_f32_e32 v73, v73, v36
	v_sub_f32_e32 v72, v72, v36
	v_sub_f32_e32 v71, v71, v36
	v_sub_f32_e32 v70, v70, v36
	v_sub_f32_e32 v69, v69, v36
	v_sub_f32_e32 v68, v68, v36
	v_sub_f32_e32 v67, v67, v36
	v_sub_f32_e32 v66, v66, v36
	v_pk_mul_f32 v[32:33], v[32:33], v[38:39] op_sel_hi:[1,0]
	v_pk_mul_f32 v[30:31], v[30:31], v[38:39] op_sel_hi:[1,0]
	v_pk_mul_f32 v[28:29], v[28:29], v[38:39] op_sel_hi:[1,0]
	v_pk_mul_f32 v[26:27], v[26:27], v[38:39] op_sel_hi:[1,0]
	v_pk_mul_f32 v[24:25], v[24:25], v[38:39] op_sel_hi:[1,0]
	v_pk_mul_f32 v[22:23], v[22:23], v[38:39] op_sel_hi:[1,0]
	v_pk_mul_f32 v[20:21], v[20:21], v[38:39] op_sel_hi:[1,0]
	v_pk_mul_f32 v[18:19], v[18:19], v[38:39] op_sel_hi:[1,0]
	v_pk_mul_f32 v[16:17], v[16:17], v[38:39] op_sel_hi:[1,0]
	v_pk_mul_f32 v[14:15], v[14:15], v[38:39] op_sel_hi:[1,0]
	v_pk_mul_f32 v[12:13], v[12:13], v[38:39] op_sel_hi:[1,0]
	v_pk_mul_f32 v[10:11], v[10:11], v[38:39] op_sel_hi:[1,0]
	v_pk_mul_f32 v[8:9], v[8:9], v[38:39] op_sel_hi:[1,0]
	v_pk_mul_f32 v[6:7], v[6:7], v[38:39] op_sel_hi:[1,0]
	v_pk_mul_f32 v[4:5], v[4:5], v[38:39] op_sel_hi:[1,0]
	v_pk_mul_f32 v[2:3], v[2:3], v[38:39] op_sel_hi:[1,0]
	v_mul_f32_e32 v136, v136, v38
	v_mov_b32_e32 v35, v34
	v_mov_b32_e32 v36, v34
	v_mov_b32_e32 v37, v34
	v_mov_b32_e32 v38, v34
	v_mov_b32_e32 v39, v34
	v_mov_b32_e32 v40, v34
	v_mov_b32_e32 v41, v34
	v_mov_b32_e32 v42, v34
	v_mov_b32_e32 v43, v34
	v_mov_b32_e32 v44, v34
	v_mov_b32_e32 v45, v34
	v_mov_b32_e32 v46, v34
	v_mov_b32_e32 v47, v34
	v_mov_b32_e32 v48, v34
	v_mov_b32_e32 v49, v34
	v_mov_b32_e32 v50, v34
	v_mov_b32_e32 v51, v34
	v_mov_b32_e32 v52, v34
	v_mov_b32_e32 v53, v34
	v_mov_b32_e32 v54, v34
	v_mov_b32_e32 v55, v34
	v_mov_b32_e32 v56, v34
	v_mov_b32_e32 v57, v34
	v_mov_b32_e32 v58, v34
	v_mov_b32_e32 v59, v34
	v_mov_b32_e32 v60, v34
	v_mov_b32_e32 v61, v34
	v_mov_b32_e32 v62, v34
	v_mov_b32_e32 v63, v34
	v_mov_b32_e32 v64, v34
	v_mov_b32_e32 v65, v34
	s_branch .LBB0_427
.LBB0_426:
.LBB0_427:
	s_setprio 0
	s_add_i32 s60, s57, 4
	s_and_b32 s61, s58, 0xf00000
	s_and_b32 s60, s60, 3
	s_lshl_b32 s78, s61, 1
	v_lshl_add_u64 v[238:239], v[128:129], 0, s[78:79]
	s_lshl_b32 s62, s60, 16
	s_mov_b32 s63, s79
	s_add_i32 s61, s59, s27
	v_lshl_add_u64 v[238:239], v[238:239], 0, s[62:63]
	s_mov_b32 m0, s61
	s_waitcnt vmcnt(0)
	s_barrier
	s_setprio 3
	v_add_u32_e32 v158, s53, v134
	ds_read_b128 v[138:141], v158
	ds_read_b128 v[240:243], v158 offset:2048
	ds_read_b128 v[244:247], v158 offset:4096
	ds_read_b128 v[248:251], v158 offset:6144
	ds_read_b128 v[252:255], v158 offset:8192
	global_load_lds_dwordx4 v[238:239], off
	s_and_b64 vcc, exec, s[40:41]
	s_cbranch_vccnz .LBB0_429
	v_lshl_add_u64 v[238:239], v[124:125], 0, s[78:79]
	s_mul_i32 s40, s60, 0x38000
	s_mov_b32 s41, s79
	v_lshl_add_u64 v[238:239], v[238:239], 0, s[40:41]
	s_add_i32 s40, s59, s5
	s_add_i32 m0, s40, 0x2000
	s_nop 0
	global_load_lds_dwordx4 v[238:239], off
.LBB0_429:
	s_lshl_b32 s40, s60, 15
	v_exp_f32_e32 v137, v82
	v_exp_f32_e32 v162, v83
	v_lshl_add_u64 v[82:83], v[130:131], 0, s[78:79]
	s_lshl_b32 s78, s40, 1
	v_lshl_add_u64 v[82:83], v[82:83], 0, s[78:79]
	v_lshl_add_u64 v[82:83], v[82:83], 0, s[24:25]
	s_add_i32 m0, s61, 0x3000
	v_exp_f32_e32 v163, v84
	global_load_lds_dwordx4 v[82:83], off
	v_exp_f32_e32 v164, v85
	v_exp_f32_e32 v165, v86
	v_exp_f32_e32 v166, v87
	v_exp_f32_e32 v167, v88
	v_exp_f32_e32 v168, v89
	v_exp_f32_e32 v169, v90
	v_exp_f32_e32 v170, v91
	v_exp_f32_e32 v171, v92
	v_exp_f32_e32 v172, v93
	v_exp_f32_e32 v173, v94
	v_exp_f32_e32 v174, v95
	v_exp_f32_e32 v175, v96
	v_exp_f32_e32 v176, v97
	v_exp_f32_e32 v177, v66
	v_exp_f32_e32 v178, v67
	v_exp_f32_e32 v179, v68
	v_exp_f32_e32 v180, v69
	v_exp_f32_e32 v181, v70
	v_exp_f32_e32 v182, v71
	v_exp_f32_e32 v183, v72
	v_exp_f32_e32 v184, v73
	s_waitcnt lgkmcnt(4)
	v_mfma_f32_32x32x16_bf16 v[82:97], v[138:141], v[118:121], v[50:65]
	v_exp_f32_e32 v185, v74
	v_add_f32_e32 v74, v137, v162
	v_exp_f32_e32 v186, v75
	v_exp_f32_e32 v187, v76
	s_waitcnt lgkmcnt(3)
	v_mfma_f32_32x32x16_bf16 v[82:97], v[240:243], v[114:117], v[82:97]
	v_exp_f32_e32 v188, v77
	v_exp_f32_e32 v189, v78
	v_exp_f32_e32 v199, v79
	v_exp_f32_e32 v200, v80
	v_exp_f32_e32 v201, v81
	s_waitcnt lgkmcnt(2)
	v_mfma_f32_32x32x16_bf16 v[82:97], v[244:247], v[110:113], v[82:97]
	s_waitcnt lgkmcnt(1)
	v_mfma_f32_32x32x16_bf16 v[82:97], v[248:251], v[106:109], v[82:97]
	ds_read_b128 v[138:141], v158 offset:512
	ds_read_b128 v[66:69], v158 offset:10240
	ds_read_b128 v[142:145], v158 offset:2560
	ds_read_b128 v[146:149], v158 offset:4608
	ds_read_b128 v[150:153], v158 offset:6656
	ds_read_b128 v[154:157], v158 offset:8704
	s_setprio 2
	ds_read_b128 v[158:161], v158 offset:10752
	s_waitcnt lgkmcnt(7)
	v_mfma_f32_32x32x16_bf16 v[82:97], v[252:255], v[102:105], v[82:97]
	v_add_f32_e32 v70, v163, v74
	v_add_f32_e32 v70, v164, v70
	s_waitcnt lgkmcnt(0)
	v_mfma_f32_32x32x16_bf16 v[82:97], v[66:69], v[98:101], v[82:97]
	v_add_f32_e32 v66, v165, v70
	v_add_f32_e32 v66, v166, v66
	v_add_f32_e32 v66, v167, v66
	v_add_f32_e32 v66, v168, v66
	v_add_f32_e32 v66, v169, v66
	v_add_f32_e32 v66, v170, v66
	v_add_f32_e32 v202, v171, v66
	v_mfma_f32_32x32x16_bf16 v[66:81], v[138:141], v[118:121], v[50:65]
	v_add_f32_e32 v138, v172, v202
	v_add_f32_e32 v138, v173, v138
	v_add_f32_e32 v138, v174, v138
	v_add_f32_e32 v138, v175, v138
	v_add_f32_e32 v138, v176, v138
	v_add_f32_e32 v138, v177, v138
	v_add_f32_e32 v138, v178, v138
	v_mfma_f32_32x32x16_bf16 v[66:81], v[142:145], v[114:117], v[66:81]
	v_add_f32_e32 v138, v179, v138
	v_add_f32_e32 v138, v180, v138
	v_add_f32_e32 v138, v181, v138
	v_add_f32_e32 v138, v182, v138
	v_add_f32_e32 v138, v183, v138
	v_add_f32_e32 v138, v184, v138
	v_add_f32_e32 v138, v185, v138
	v_mfma_f32_32x32x16_bf16 v[66:81], v[146:149], v[110:113], v[66:81]
	v_add_f32_e32 v138, v186, v138
	v_add_f32_e32 v138, v187, v138
	v_add_f32_e32 v138, v188, v138
	v_add_f32_e32 v138, v189, v138
	v_add_f32_e32 v138, v199, v138
	v_add_f32_e32 v202, v200, v138
	v_cvt_pk_bf16_f32 v138, v137, v162
	v_mfma_f32_32x32x16_bf16 v[66:81], v[150:153], v[106:109], v[66:81]
	v_cvt_pk_bf16_f32 v139, v163, v164
	v_cvt_pk_bf16_f32 v140, v165, v166
	v_cvt_pk_bf16_f32 v141, v167, v168
	v_cvt_pk_bf16_f32 v142, v169, v170
	v_cvt_pk_bf16_f32 v143, v171, v172
	v_cvt_pk_bf16_f32 v144, v173, v174
	v_cvt_pk_bf16_f32 v145, v175, v176
	v_mfma_f32_32x32x16_bf16 v[66:81], v[154:157], v[102:105], v[66:81]
	v_cvt_pk_bf16_f32 v146, v177, v178
	v_cvt_pk_bf16_f32 v147, v179, v180
	v_cvt_pk_bf16_f32 v148, v181, v182
	v_cvt_pk_bf16_f32 v149, v183, v184
	v_cvt_pk_bf16_f32 v150, v185, v186
	v_cvt_pk_bf16_f32 v151, v187, v188
	v_cvt_pk_bf16_f32 v152, v189, v199
	v_mfma_f32_32x32x16_bf16 v[66:81], v[158:161], v[98:101], v[66:81]
	v_cvt_pk_bf16_f32 v153, v200, v201
	v_add_u32_e32 v137, s56, v133
	ds_read_b64_tr_b16 v[154:155], v137 offset:12288
	ds_read_b64_tr_b16 v[156:157], v137 offset:12800
	ds_read_b64_tr_b16 v[158:159], v137 offset:16384
	s_waitcnt lgkmcnt(1)
	v_mfma_f32_32x32x16_bf16 v[18:33], v[154:157], v[138:141], v[18:33]
	ds_read_b64_tr_b16 v[160:161], v137 offset:16896
	ds_read_b64_tr_b16 v[154:155], v137 offset:13312
	s_waitcnt lgkmcnt(1)
	v_mfma_f32_32x32x16_bf16 v[2:17], v[158:161], v[138:141], v[2:17]
	ds_read_b64_tr_b16 v[156:157], v137 offset:13824
	ds_read_b64_tr_b16 v[138:139], v137 offset:17408
	s_waitcnt lgkmcnt(1)
	v_mfma_f32_32x32x16_bf16 v[18:33], v[154:157], v[142:145], v[18:33]
	ds_read_b64_tr_b16 v[140:141], v137 offset:17920
	ds_read_b64_tr_b16 v[154:155], v137 offset:14336
	s_waitcnt lgkmcnt(1)
	s_setprio 1
	v_mfma_f32_32x32x16_bf16 v[2:17], v[138:141], v[142:145], v[2:17]
	ds_read_b64_tr_b16 v[156:157], v137 offset:14848
	ds_read_b64_tr_b16 v[138:139], v137 offset:15360
	ds_read_b64_tr_b16 v[140:141], v137 offset:15872
	ds_read_b64_tr_b16 v[142:143], v137 offset:18432
	ds_read_b64_tr_b16 v[144:145], v137 offset:18944
	ds_read_b64_tr_b16 v[158:159], v137 offset:19456
	ds_read_b64_tr_b16 v[160:161], v137 offset:19968
	v_max_f32_e32 v137, v67, v67
	s_waitcnt lgkmcnt(6)
	v_mfma_f32_32x32x16_bf16 v[18:33], v[154:157], v[146:149], v[18:33]
	v_max_f32_e32 v154, v83, v83
	v_max_f32_e32 v137, v154, v137
	v_max3_f32 v154, v82, v66, v84
	v_max3_f32 v137, v137, v85, v69
	v_max3_f32 v154, v154, v68, v86
	v_max3_f32 v137, v137, v87, v71
	v_max3_f32 v137, v137, v89, v73
	s_waitcnt lgkmcnt(2)
	v_mfma_f32_32x32x16_bf16 v[2:17], v[142:145], v[146:149], v[2:17]
	v_max3_f32 v142, v154, v70, v88
	v_max3_f32 v142, v142, v72, v90
	v_max3_f32 v137, v137, v91, v75
	v_max3_f32 v142, v142, v74, v92
	v_max3_f32 v137, v137, v93, v77
	v_max3_f32 v142, v142, v76, v94
	v_max3_f32 v137, v137, v95, v79
	v_mfma_f32_32x32x16_bf16 v[18:33], v[138:141], v[150:153], v[18:33]
	v_max3_f32 v138, v142, v78, v96
	v_max3_f32 v137, v137, v97, v81
	v_add_f32_e32 v139, v201, v202
	v_max3_f32 v137, v138, v80, v137
	v_add_f32_e32 v136, v136, v139
	v_cmp_lt_f32_e32 vcc, s33, v137
	s_waitcnt lgkmcnt(0)
	v_mfma_f32_32x32x16_bf16 v[2:17], v[158:161], v[150:153], v[2:17]
	s_cbranch_vccz .LBB0_431
	v_mov_b32_e32 v34, v137
	s_nop 1
	v_permlane32_swap_b32 v137, v34
	s_nop 1
	s_nop 0
	v_max3_f32 v36, v137, v34, 0
	v_exp_f32_e64 v38, -v36
	v_add_f32_e32 v135, v135, v36
	v_xor_b32_e32 v34, 0x80000000, v135
	v_pk_add_f32 v[82:83], v[82:83], v[36:37] op_sel_hi:[1,0] neg_lo:[0,1] neg_hi:[0,1]
	v_pk_add_f32 v[84:85], v[84:85], v[36:37] op_sel_hi:[1,0] neg_lo:[0,1] neg_hi:[0,1]
	v_pk_add_f32 v[86:87], v[86:87], v[36:37] op_sel_hi:[1,0] neg_lo:[0,1] neg_hi:[0,1]
	v_pk_add_f32 v[88:89], v[88:89], v[36:37] op_sel_hi:[1,0] neg_lo:[0,1] neg_hi:[0,1]
	v_pk_add_f32 v[90:91], v[90:91], v[36:37] op_sel_hi:[1,0] neg_lo:[0,1] neg_hi:[0,1]
	v_pk_add_f32 v[92:93], v[92:93], v[36:37] op_sel_hi:[1,0] neg_lo:[0,1] neg_hi:[0,1]
	v_pk_add_f32 v[94:95], v[94:95], v[36:37] op_sel_hi:[1,0] neg_lo:[0,1] neg_hi:[0,1]
	v_pk_add_f32 v[96:97], v[96:97], v[36:37] op_sel_hi:[1,0] neg_lo:[0,1] neg_hi:[0,1]
	v_sub_f32_e32 v81, v81, v36
	v_sub_f32_e32 v80, v80, v36
	v_sub_f32_e32 v79, v79, v36
	v_sub_f32_e32 v78, v78, v36
	v_sub_f32_e32 v77, v77, v36
	v_sub_f32_e32 v76, v76, v36
	v_sub_f32_e32 v75, v75, v36
	v_sub_f32_e32 v74, v74, v36
	v_sub_f32_e32 v73, v73, v36
	v_sub_f32_e32 v72, v72, v36
	v_sub_f32_e32 v71, v71, v36
	v_sub_f32_e32 v70, v70, v36
	v_sub_f32_e32 v69, v69, v36
	v_sub_f32_e32 v68, v68, v36
	v_sub_f32_e32 v67, v67, v36
	v_sub_f32_e32 v66, v66, v36
	v_pk_mul_f32 v[32:33], v[32:33], v[38:39] op_sel_hi:[1,0]
	v_pk_mul_f32 v[30:31], v[30:31], v[38:39] op_sel_hi:[1,0]
	v_pk_mul_f32 v[28:29], v[28:29], v[38:39] op_sel_hi:[1,0]
	v_pk_mul_f32 v[26:27], v[26:27], v[38:39] op_sel_hi:[1,0]
	v_pk_mul_f32 v[24:25], v[24:25], v[38:39] op_sel_hi:[1,0]
	v_pk_mul_f32 v[22:23], v[22:23], v[38:39] op_sel_hi:[1,0]
	v_pk_mul_f32 v[20:21], v[20:21], v[38:39] op_sel_hi:[1,0]
	v_pk_mul_f32 v[18:19], v[18:19], v[38:39] op_sel_hi:[1,0]
	v_pk_mul_f32 v[16:17], v[16:17], v[38:39] op_sel_hi:[1,0]
	v_pk_mul_f32 v[14:15], v[14:15], v[38:39] op_sel_hi:[1,0]
	v_pk_mul_f32 v[12:13], v[12:13], v[38:39] op_sel_hi:[1,0]
	v_pk_mul_f32 v[10:11], v[10:11], v[38:39] op_sel_hi:[1,0]
	v_pk_mul_f32 v[8:9], v[8:9], v[38:39] op_sel_hi:[1,0]
	v_pk_mul_f32 v[6:7], v[6:7], v[38:39] op_sel_hi:[1,0]
	v_pk_mul_f32 v[4:5], v[4:5], v[38:39] op_sel_hi:[1,0]
	v_pk_mul_f32 v[2:3], v[2:3], v[38:39] op_sel_hi:[1,0]
	v_mul_f32_e32 v136, v136, v38
	v_mov_b32_e32 v35, v34
	v_mov_b32_e32 v36, v34
	v_mov_b32_e32 v37, v34
	v_mov_b32_e32 v38, v34
	v_mov_b32_e32 v39, v34
	v_mov_b32_e32 v40, v34
	v_mov_b32_e32 v41, v34
	v_mov_b32_e32 v42, v34
	v_mov_b32_e32 v43, v34
	v_mov_b32_e32 v44, v34
	v_mov_b32_e32 v45, v34
	v_mov_b32_e32 v46, v34
	v_mov_b32_e32 v47, v34
	v_mov_b32_e32 v48, v34
	v_mov_b32_e32 v49, v34
	v_mov_b32_e32 v50, v34
	v_mov_b32_e32 v51, v34
	v_mov_b32_e32 v52, v34
	v_mov_b32_e32 v53, v34
	v_mov_b32_e32 v54, v34
	v_mov_b32_e32 v55, v34
	v_mov_b32_e32 v56, v34
	v_mov_b32_e32 v57, v34
	v_mov_b32_e32 v58, v34
	v_mov_b32_e32 v59, v34
	v_mov_b32_e32 v60, v34
	v_mov_b32_e32 v61, v34
	v_mov_b32_e32 v62, v34
	v_mov_b32_e32 v63, v34
	v_mov_b32_e32 v64, v34
	v_mov_b32_e32 v65, v34

	.amdhsa_kernel _Z10fwd_kernel4Args
		.amdhsa_group_segment_fixed_size 0
		.amdhsa_private_segment_fixed_size 0
		.amdhsa_kernarg_size 400
		.amdhsa_user_sgpr_count 2
		.amdhsa_user_sgpr_dispatch_ptr 0
		.amdhsa_user_sgpr_queue_ptr 0
		.amdhsa_user_sgpr_kernarg_segment_ptr 1
		.amdhsa_user_sgpr_dispatch_id 0
		.amdhsa_user_sgpr_kernarg_preload_length 0
		.amdhsa_user_sgpr_kernarg_preload_offset 0
		.amdhsa_user_sgpr_private_segment_size 0
		.amdhsa_uses_dynamic_stack 0
		.amdhsa_enable_private_segment 0
		.amdhsa_system_sgpr_workgroup_id_x 1
		.amdhsa_system_sgpr_workgroup_id_y 0
		.amdhsa_system_sgpr_workgroup_id_z 0
		.amdhsa_system_sgpr_workgroup_info 0
		.amdhsa_system_vgpr_workitem_id 2
		.amdhsa_next_free_vgpr 256
		.amdhsa_next_free_sgpr 102
		.amdhsa_accum_offset 256
		.amdhsa_reserve_vcc 1
		.amdhsa_float_round_mode_32 0
		.amdhsa_float_round_mode_16_64 0
		.amdhsa_float_denorm_mode_32 3
		.amdhsa_float_denorm_mode_16_64 3
		.amdhsa_dx10_clamp 1
		.amdhsa_ieee_mode 1
		.amdhsa_fp16_overflow 0
		.amdhsa_tg_split 0
		.amdhsa_exception_fp_ieee_invalid_op 0
		.amdhsa_exception_fp_denorm_src 0
		.amdhsa_exception_fp_ieee_div_zero 0
		.amdhsa_exception_fp_ieee_overflow 0
		.amdhsa_exception_fp_ieee_underflow 0
		.amdhsa_exception_fp_ieee_inexact 0
		.amdhsa_exception_int_div_zero 0
	.end_amdhsa_kernel

amdhsa.kernels:
  - .agpr_count:     0
    .args:
      - .offset:         0
        .size:           144
        .value_kind:     by_value
      - .offset:         144
        .size:           4
        .value_kind:     hidden_block_count_x
      - .offset:         148
        .size:           4
        .value_kind:     hidden_block_count_y
      - .offset:         152
        .size:           4
        .value_kind:     hidden_block_count_z
      - .offset:         156
        .size:           2
        .value_kind:     hidden_group_size_x
      - .offset:         158
        .size:           2
        .value_kind:     hidden_group_size_y
      - .offset:         160
        .size:           2
        .value_kind:     hidden_group_size_z
      - .offset:         162
        .size:           2
        .value_kind:     hidden_remainder_x
      - .offset:         164
        .size:           2
        .value_kind:     hidden_remainder_y
      - .offset:         166
        .size:           2
        .value_kind:     hidden_remainder_z
      - .offset:         184
        .size:           8
        .value_kind:     hidden_global_offset_x
      - .offset:         192
        .size:           8
        .value_kind:     hidden_global_offset_y
      - .offset:         200
        .size:           8
        .value_kind:     hidden_global_offset_z
      - .offset:         208
        .size:           2
        .value_kind:     hidden_grid_dims
      - .offset:         232
        .size:           8
        .value_kind:     hidden_multigrid_sync_arg
      - .offset:         264
        .size:           4
        .value_kind:     hidden_dynamic_lds_size
    .group_segment_fixed_size: 0
    .kernarg_segment_align: 8
    .kernarg_segment_size: 400
    .language:       OpenCL C
    .language_version:
      - 2
      - 0
    .max_flat_workgroup_size: 512
    .name:           _Z10fwd_kernel4Args
    .private_segment_fixed_size: 0
    .sgpr_count:     108
    .sgpr_spill_count: 216
    .symbol:         _Z10fwd_kernel4Args.kd
    .uniform_work_group_size: 1
    .uses_dynamic_stack: false
    .vgpr_count:     256
    .vgpr_spill_count: 0
    .wavefront_size: 64
